# k5 plus layer-0 norm loop rewritten: g loaded once before the loop, scale/shift loads issued at item top before the next-row prefetch, counted vmcnt so the prefetch stays in flight (was: 4 exposed loa
# baseline (speedup 1.0000x reference)
.LBB0_593:
	s_cmp_lt_i32 s96, 3
	s_cselect_b64 s[0:1], -1, 0
	s_and_b64 s[4:5], s[0:1], s[4:5]
	s_andn2_b64 vcc, exec, s[4:5]
	s_cbranch_vccnz .LBB0_603
	s_add_i32 s3, 0, 0x25490
	v_mov_b32_e32 v1, s3
	s_waitcnt vmcnt(0)
	ds_read_b64 v[2:3], v1
	s_add_i32 s4, 0, 0x254a0
	s_add_i32 s5, 0, 0x254c0
	s_add_i32 s6, 0, 0x25588
	s_add_i32 s7, 0, 0x25628
	v_mov_b32_e32 v1, s4
	v_mov_b32_e32 v6, s5
	v_mov_b32_e32 v8, s6
	ds_read_b64 v[4:5], v1
	ds_read_b64 v[6:7], v6
	ds_read_b64 v[8:9], v8
	v_mov_b32_e32 v1, s7
	s_waitcnt lgkmcnt(3)
	v_readfirstlane_b32 s3, v3
	v_readfirstlane_b32 s10, v2
	ds_read_b64 v[2:3], v1
	s_cmpk_gt_i32 s2, 0x10ff
	s_waitcnt lgkmcnt(3)
	v_readfirstlane_b32 s11, v5
	v_readfirstlane_b32 s16, v4
	s_waitcnt lgkmcnt(2)
	v_readfirstlane_b32 s9, v7
	v_readfirstlane_b32 s8, v6
	s_waitcnt lgkmcnt(1)
	v_readfirstlane_b32 s5, v9
	v_readfirstlane_b32 s4, v8
	s_waitcnt lgkmcnt(0)
	v_readfirstlane_b32 s7, v3
	v_readfirstlane_b32 s6, v2
	v_mov_b32_e32 v2, v0
	s_cbranch_scc1 .LBB0_603
	v_ashrrev_i32_e32 v1, 8, v2
	s_lshl_b32 s17, s2, 1
	v_add_u32_e32 v3, s17, v1
	s_movk_i32 s18, 0x2000
	v_add_u32_e32 v4, 0xffffe000, v3
	v_cmp_gt_i32_e32 vcc, s18, v3
	v_ashrrev_i32_e32 v5, 31, v3
	v_mov_b32_e32 v6, s3
	v_cndmask_b32_e32 v4, v4, v3, vcc
	v_mov_b32_e32 v3, s11
	v_cndmask_b32_e32 v5, 0, v5, vcc
	v_cndmask_b32_e32 v7, v3, v6, vcc
	v_mov_b32_e32 v3, s16
	v_mov_b32_e32 v6, s10
	v_lshlrev_b32_e32 v2, 2, v2
	v_cndmask_b32_e32 v6, v3, v6, vcc
	v_lshlrev_b64 v[4:5], 14, v[4:5]
	v_and_b32_e32 v36, 0x3fc, v2
	v_mov_b32_e32 v35, 0
	v_lshl_add_u64 v[4:5], v[6:7], 0, v[4:5]
	v_lshlrev_b32_e32 v34, 2, v36
	v_lshl_add_u64 v[14:15], v[4:5], 0, v[34:35]
	v_add_co_u32_e32 v2, vcc, s18, v14
	s_movk_i32 s19, 0x3000
	s_nop 0
	v_addc_co_u32_e32 v3, vcc, 0, v15, vcc
	v_add_co_u32_e32 v16, vcc, s19, v14
	global_load_dwordx4 v[10:13], v[2:3], off offset:-4096
	global_load_dwordx4 v[6:9], v[2:3], off
	v_addc_co_u32_e32 v17, vcc, 0, v15, vcc
	global_load_dwordx4 v[18:21], v[14:15], off
	global_load_dwordx4 v[2:5], v[16:17], off
	v_mbcnt_lo_u32_b32 v14, -1, 0
	v_mbcnt_hi_u32_b32 v14, -1, v14
	v_and_b32_e32 v15, 64, v14
	v_add_u32_e32 v15, 64, v15
	v_xor_b32_e32 v16, 32, v14
	v_cmp_lt_i32_e32 vcc, v16, v15
	v_lshl_add_u64 v[38:39], s[8:9], 0, v[34:35]
	v_or_b32_e32 v40, 0x800, v36
	v_cndmask_b32_e32 v16, v14, v16, vcc
	v_lshlrev_b32_e32 v37, 2, v16
	v_xor_b32_e32 v16, 16, v14
	v_cmp_lt_i32_e32 vcc, v16, v15
	v_or_b32_e32 v42, 0xc00, v36
	s_lshl_b32 s21, s24, 1
	v_cndmask_b32_e32 v16, v14, v16, vcc
	v_lshlrev_b32_e32 v41, 2, v16
	v_xor_b32_e32 v16, 8, v14
	v_cmp_lt_i32_e32 vcc, v16, v15
	v_mov_b32_e32 v59, 0x358637bd
	s_mov_b32 s22, 0x800000
	v_cndmask_b32_e32 v16, v14, v16, vcc
	v_lshlrev_b32_e32 v43, 2, v16
	v_xor_b32_e32 v16, 4, v14
	v_cmp_lt_i32_e32 vcc, v16, v15
	s_movk_i32 s23, 0x7fff
	s_mov_b32 s25, 0xffff0000
	v_cndmask_b32_e32 v16, v14, v16, vcc
	v_lshlrev_b32_e32 v56, 2, v16
	v_xor_b32_e32 v16, 2, v14
	v_cmp_lt_i32_e32 vcc, v16, v15
	s_mov_b32 s26, s2
	s_nop 0
	v_cndmask_b32_e32 v16, v14, v16, vcc
	v_lshlrev_b32_e32 v57, 2, v16
	v_xor_b32_e32 v16, 1, v14
	v_cmp_lt_i32_e32 vcc, v16, v15
	s_nop 1
	v_cndmask_b32_e32 v14, v14, v16, vcc
	v_lshlrev_b32_e32 v58, 2, v14
	v_or_b32_e32 v14, 0x400, v36
	v_lshlrev_b32_e32 v34, 2, v14
	v_lshl_add_u64 v[44:45], s[8:9], 0, v[34:35]
	v_lshlrev_b32_e32 v34, 2, v40
	v_lshl_add_u64 v[46:47], s[8:9], 0, v[34:35]
	v_lshlrev_b32_e32 v34, 2, v42
	v_lshl_add_u64 v[48:49], s[8:9], 0, v[34:35]
	s_add_i32 s8, s2, s24
	s_lshl_b32 s20, s8, 1
	s_mov_b64 s[8:9], 0x4000
	v_lshlrev_b32_e32 v50, 2, v14
	s_mov_b64 s[98:99], 0x1000
	s_mov_b64 s[100:101], 0x3000
	global_load_dwordx4 v[104:107], v[38:39], off
	global_load_dwordx4 v[108:111], v[44:45], off
	global_load_dwordx4 v[112:115], v[46:47], off
	global_load_dwordx4 v[116:119], v[48:49], off
	s_branch .LBB0_597
.LBB0_596:
	s_or_b64 exec, exec, s[14:15]
	s_waitcnt lgkmcnt(0)
	s_barrier
	s_waitcnt lgkmcnt(0)
	v_ashrrev_i32_e32 v34, 6, v51
	v_lshlrev_b32_e32 v34, 2, v34
	v_and_b32_e32 v51, -16, v34
	v_add_u32_e32 v51, 0, v51
	ds_read_b96 v[72:74], v51
	v_or_b32_e32 v34, 12, v34
	v_add_u32_e32 v34, 0, v34
	v_lshlrev_b64 v[54:55], 13, v[54:55]
	v_mov_b32_e32 v51, v35
	s_waitcnt lgkmcnt(0)
	v_mov_b32_e32 v78, v73
	ds_read_b32 v73, v34
	v_mov_b32_e32 v79, v74
	v_add_u32_e32 v1, s21, v1
	s_waitcnt lgkmcnt(0)
	v_pk_add_f32 v[72:73], v[78:79], v[72:73]
	s_nop 0
	v_add_f32_e32 v34, v72, v73
	v_fmamk_f32 v34, v34, 0x39800000, v59
	v_mul_f32_e32 v72, 0x4b800000, v34
	v_cmp_gt_f32_e32 vcc, s22, v34
	s_nop 1
	v_cndmask_b32_e32 v34, v34, v72, vcc
	v_rsq_f32_e32 v74, v34
	v_lshl_add_u64 v[72:73], s[4:5], 0, v[54:55]
	v_lshlrev_b32_e32 v34, 1, v36
	v_lshl_add_u64 v[54:55], v[72:73], 0, v[34:35]
	v_mul_f32_e32 v34, 0x45800000, v74
	v_cndmask_b32_e32 v74, v74, v34, vcc
	v_pk_mul_f32 v[20:21], v[20:21], v[74:75] op_sel_hi:[1,0]
	v_pk_mul_f32 v[18:19], v[18:19], v[74:75] op_sel_hi:[1,0]
	v_pk_mul_f32 v[12:13], v[12:13], v[74:75] op_sel_hi:[1,0]
	v_pk_mul_f32 v[10:11], v[10:11], v[74:75] op_sel_hi:[1,0]
	v_pk_mul_f32 v[8:9], v[8:9], v[74:75] op_sel_hi:[1,0]
	v_pk_mul_f32 v[6:7], v[6:7], v[74:75] op_sel_hi:[1,0]
	v_pk_mul_f32 v[70:71], v[4:5], v[74:75] op_sel_hi:[1,0]
	v_pk_mul_f32 v[76:77], v[2:3], v[74:75] op_sel_hi:[1,0]
	s_andn2_b64 vcc, exec, s[12:13]
	s_waitcnt vmcnt(4)
	s_cbranch_vccnz .Ln0_vec_ready
	s_waitcnt vmcnt(0)
.Ln0_vec_ready:
	v_pk_mul_f32 v[18:19], v[104:105], v[18:19]
	v_pk_mul_f32 v[20:21], v[106:107], v[20:21]
	v_pk_add_f32 v[60:61], v[122:123], 1.0 op_sel_hi:[1,0]
	v_pk_add_f32 v[62:63], v[120:121], 1.0 op_sel_hi:[1,0]
	v_pk_fma_f32 v[20:21], v[60:61], v[20:21], v[138:139]
	v_pk_fma_f32 v[18:19], v[62:63], v[18:19], v[136:137]
	v_cvt_pk_bf16_f32 v18, v18, v19
	v_cvt_pk_bf16_f32 v19, v20, v21
	global_store_dwordx2 v[54:55], v[18:19], off
	v_pk_mul_f32 v[10:11], v[108:109], v[10:11]
	v_pk_mul_f32 v[12:13], v[110:111], v[12:13]
	v_pk_add_f32 v[60:61], v[126:127], 1.0 op_sel_hi:[1,0]
	v_pk_add_f32 v[62:63], v[124:125], 1.0 op_sel_hi:[1,0]
	v_pk_fma_f32 v[12:13], v[60:61], v[12:13], v[142:143]
	v_pk_fma_f32 v[10:11], v[62:63], v[10:11], v[140:141]
	v_cvt_pk_bf16_f32 v10, v10, v11
	v_cvt_pk_bf16_f32 v11, v12, v13
	global_store_dwordx2 v[54:55], v[10:11], off offset:2048
	v_lshlrev_b32_e32 v34, 1, v40
	v_lshl_add_u64 v[54:55], v[72:73], 0, v[34:35]
	v_pk_mul_f32 v[6:7], v[112:113], v[6:7]
	v_pk_mul_f32 v[8:9], v[114:115], v[8:9]
	v_pk_add_f32 v[60:61], v[130:131], 1.0 op_sel_hi:[1,0]
	v_pk_add_f32 v[62:63], v[128:129], 1.0 op_sel_hi:[1,0]
	v_pk_fma_f32 v[8:9], v[60:61], v[8:9], v[146:147]
	v_pk_fma_f32 v[6:7], v[62:63], v[6:7], v[144:145]
	v_cvt_pk_bf16_f32 v6, v6, v7
	v_cvt_pk_bf16_f32 v7, v8, v9
	global_store_dwordx2 v[54:55], v[6:7], off
	v_lshlrev_b32_e32 v34, 1, v42
	v_lshl_add_u64 v[68:69], v[72:73], 0, v[34:35]
	v_pk_mul_f32 v[164:165], v[76:77], v[116:117]
	v_pk_mul_f32 v[166:167], v[70:71], v[118:119]
	v_pk_add_f32 v[60:61], v[134:135], 1.0 op_sel_hi:[1,0]
	v_pk_add_f32 v[62:63], v[132:133], 1.0 op_sel_hi:[1,0]
	v_pk_fma_f32 v[166:167], v[166:167], v[60:61], v[150:151]
	v_pk_fma_f32 v[164:165], v[164:165], v[62:63], v[148:149]
	v_cvt_pk_bf16_f32 v164, v164, v165
	v_cvt_pk_bf16_f32 v165, v166, v167
	global_store_dwordx2 v[68:69], v[164:165], off
	s_waitcnt vmcnt(4)
	v_mov_b32_e32 v10, v22
	v_mov_b32_e32 v11, v23
	v_mov_b32_e32 v12, v24
	v_mov_b32_e32 v13, v25
	v_mov_b32_e32 v6, v26
	v_mov_b32_e32 v7, v27
	v_mov_b32_e32 v8, v28
	v_mov_b32_e32 v9, v29
	v_mov_b32_e32 v18, v30
	v_mov_b32_e32 v19, v31
	v_mov_b32_e32 v20, v32
	v_mov_b32_e32 v21, v33
	v_mov_b32_e32 v2, v14
	v_mov_b32_e32 v3, v15
	v_mov_b32_e32 v4, v16
	v_mov_b32_e32 v5, v17
	s_cbranch_vccz .LBB0_603
.LBB0_597:
	v_add_u32_e32 v54, s17, v1
	v_cmp_gt_i32_e32 vcc, s18, v54
	v_mov_b64_e32 v[52:53], 0x6000
	v_ashrrev_i32_e32 v55, 31, v54
	s_and_saveexec_b64 s[12:13], vcc
	v_lshrrev_b32_e32 v14, 20, v55
	v_add_u32_e32 v14, v54, v14
	v_ashrrev_i32_e32 v14, 12, v14
	v_mul_i32_i24_e32 v52, 0x3000, v14
	v_ashrrev_i32_e32 v53, 31, v52
	s_or_b64 exec, exec, s[12:13]
	s_add_i32 s26, s26, s24
	s_cmpk_gt_i32 s26, 0x10ff
	s_cselect_b64 s[12:13], -1, 0
	s_and_b64 vcc, exec, s[12:13]
	v_lshlrev_b32_e32 v34, 2, v36
	s_waitcnt vmcnt(4)
	v_mov_b32_e32 v30, v18
	v_mov_b32_e32 v31, v19
	v_mov_b32_e32 v32, v20
	v_mov_b32_e32 v33, v21
	v_mov_b32_e32 v22, v10
	v_mov_b32_e32 v23, v11
	v_mov_b32_e32 v24, v12
	v_mov_b32_e32 v25, v13
	v_mov_b32_e32 v26, v6
	v_mov_b32_e32 v27, v7
	v_mov_b32_e32 v28, v8
	v_mov_b32_e32 v29, v9
	v_mov_b32_e32 v14, v2
	v_mov_b32_e32 v15, v3
	v_mov_b32_e32 v16, v4
	v_mov_b32_e32 v17, v5
	v_lshl_add_u64 v[152:153], v[52:53], 2, s[6:7]
	v_lshl_add_u64 v[152:153], v[152:153], 0, v[34:35]
	v_lshl_add_u64 v[154:155], v[152:153], 0, s[8:9]
	v_lshl_add_u64 v[156:157], v[152:153], 0, s[98:99]
	v_lshl_add_u64 v[158:159], v[152:153], 0, s[100:101]
	v_lshl_add_u64 v[160:161], v[154:155], 0, s[98:99]
	v_lshl_add_u64 v[162:163], v[154:155], 0, s[100:101]
	global_load_dwordx4 v[120:123], v[160:161], off offset:-4096
	global_load_dwordx4 v[124:127], v[160:161], off
	global_load_dwordx4 v[128:131], v[162:163], off offset:-4096
	global_load_dwordx4 v[132:135], v[162:163], off
	global_load_dwordx4 v[136:139], v[156:157], off offset:-4096
	global_load_dwordx4 v[140:143], v[156:157], off
	global_load_dwordx4 v[144:147], v[158:159], off offset:-4096
	global_load_dwordx4 v[148:151], v[158:159], off
	s_cbranch_vccnz .LBB0_601
	v_add_u32_e32 v14, s20, v1
	v_add_u32_e32 v16, 0xffffe000, v14
	v_cmp_gt_i32_e32 vcc, s18, v14
	v_ashrrev_i32_e32 v15, 31, v14
	v_mov_b32_e32 v17, s3
	v_cndmask_b32_e32 v14, v16, v14, vcc
	v_mov_b32_e32 v16, s11
	v_cndmask_b32_e32 v15, 0, v15, vcc
	v_cndmask_b32_e32 v17, v16, v17, vcc
	v_mov_b32_e32 v16, s16
	v_mov_b32_e32 v22, s10
	v_cndmask_b32_e32 v16, v16, v22, vcc
	v_lshlrev_b64 v[14:15], 14, v[14:15]
	v_lshl_add_u64 v[14:15], v[16:17], 0, v[14:15]
	v_lshl_add_u64 v[60:61], v[14:15], 0, v[34:35]
	v_add_co_u32_e32 v14, vcc, s18, v60
	s_nop 1
	v_addc_co_u32_e32 v15, vcc, 0, v61, vcc
	v_add_co_u32_e32 v62, vcc, s19, v60
	global_load_dwordx4 v[22:25], v[14:15], off offset:-4096
	global_load_dwordx4 v[26:29], v[14:15], off
	v_addc_co_u32_e32 v63, vcc, 0, v61, vcc
	global_load_dwordx4 v[30:33], v[60:61], off
	global_load_dwordx4 v[14:17], v[62:63], off

	.amdhsa_kernel _Z4mega2MP
		.amdhsa_group_segment_fixed_size 0
		.amdhsa_private_segment_fixed_size 0
		.amdhsa_kernarg_size 808
		.amdhsa_user_sgpr_count 2
		.amdhsa_user_sgpr_dispatch_ptr 0
		.amdhsa_user_sgpr_queue_ptr 0
		.amdhsa_user_sgpr_kernarg_segment_ptr 1
		.amdhsa_user_sgpr_dispatch_id 0
		.amdhsa_user_sgpr_kernarg_preload_length 0
		.amdhsa_user_sgpr_kernarg_preload_offset 0
		.amdhsa_user_sgpr_private_segment_size 0
		.amdhsa_uses_dynamic_stack 0
		.amdhsa_enable_private_segment 0
		.amdhsa_system_sgpr_workgroup_id_x 1
		.amdhsa_system_sgpr_workgroup_id_y 0
		.amdhsa_system_sgpr_workgroup_id_z 0
		.amdhsa_system_sgpr_workgroup_info 0
		.amdhsa_system_vgpr_workitem_id 0
		.amdhsa_next_free_vgpr 239
		.amdhsa_next_free_sgpr 102
		.amdhsa_accum_offset 240
		.amdhsa_reserve_vcc 1
		.amdhsa_float_round_mode_32 0
		.amdhsa_float_round_mode_16_64 0
		.amdhsa_float_denorm_mode_32 3
		.amdhsa_float_denorm_mode_16_64 3
		.amdhsa_dx10_clamp 1
		.amdhsa_ieee_mode 1
		.amdhsa_fp16_overflow 0
		.amdhsa_tg_split 0
		.amdhsa_exception_fp_ieee_invalid_op 0
		.amdhsa_exception_fp_denorm_src 0
		.amdhsa_exception_fp_ieee_div_zero 0
		.amdhsa_exception_fp_ieee_overflow 0
		.amdhsa_exception_fp_ieee_underflow 0
		.amdhsa_exception_fp_ieee_inexact 0
		.amdhsa_exception_int_div_zero 0
	.end_amdhsa_kernel

amdhsa.kernels:
  - .agpr_count:     0
    .args:
      - .offset:         0
        .size:           552
        .value_kind:     by_value
      - .offset:         552
        .size:           4
        .value_kind:     hidden_block_count_x
      - .offset:         556
        .size:           4
        .value_kind:     hidden_block_count_y
      - .offset:         560
        .size:           4
        .value_kind:     hidden_block_count_z
      - .offset:         564
        .size:           2
        .value_kind:     hidden_group_size_x
      - .offset:         566
        .size:           2
        .value_kind:     hidden_group_size_y
      - .offset:         568
        .size:           2
        .value_kind:     hidden_group_size_z
      - .offset:         570
        .size:           2
        .value_kind:     hidden_remainder_x
      - .offset:         572
        .size:           2
        .value_kind:     hidden_remainder_y
      - .offset:         574
        .size:           2
        .value_kind:     hidden_remainder_z
      - .offset:         592
        .size:           8
        .value_kind:     hidden_global_offset_x
      - .offset:         600
        .size:           8
        .value_kind:     hidden_global_offset_y
      - .offset:         608
        .size:           8
        .value_kind:     hidden_global_offset_z
      - .offset:         616
        .size:           2
        .value_kind:     hidden_grid_dims
      - .offset:         672
        .size:           4
        .value_kind:     hidden_dynamic_lds_size
    .group_segment_fixed_size: 0
    .kernarg_segment_align: 8
    .kernarg_segment_size: 808
    .language:       OpenCL C
    .language_version:
      - 2
      - 0
    .max_flat_workgroup_size: 512
    .name:           _Z4mega2MP
    .private_segment_fixed_size: 0
    .sgpr_count:     108
    .sgpr_spill_count: 30
    .symbol:         _Z4mega2MP.kd
    .uniform_work_group_size: 1
    .uses_dynamic_stack: false
    .vgpr_count:     239
    .vgpr_spill_count: 0
    .wavefront_size: 64
